# attention loop: V-fragment addresses and the first 4 V reads issued right after the QK MFMAs (before the softmax block) instead of after the P conversion
# speedup vs baseline: 1.0065x; 1.0054x over previous
.LBB0_267:
	s_bitcmp1_b32 s4, 0
	s_cselect_b32 s5, 0x8c00, 0
	v_xor_b32_e32 v66, 0x80000000, v154
	s_nop 0
	v_or_b32_e32 v67, s5, v146
	v_add_u32_e32 v172, v67, v183
	ds_read_b128 v[206:209], v172
	ds_read_b128 v[210:213], v172 offset:4608
	ds_read_b128 v[222:225], v172 offset:32
	ds_read_b128 v[238:241], v172 offset:4640
	ds_read_b128 v[242:245], v172 offset:64
	v_mov_b32_e32 v67, v66
	v_mov_b32_e32 v68, v66
	v_mov_b32_e32 v69, v66
	v_mov_b32_e32 v70, v66
	v_mov_b32_e32 v71, v66
	v_mov_b32_e32 v72, v66
	v_mov_b32_e32 v73, v66
	v_mov_b32_e32 v74, v66
	v_mov_b32_e32 v75, v66
	v_mov_b32_e32 v76, v66
	v_mov_b32_e32 v77, v66
	v_mov_b32_e32 v78, v66
	v_mov_b32_e32 v79, v66
	v_mov_b32_e32 v80, v66
	v_mov_b32_e32 v81, v66
	s_waitcnt lgkmcnt(4)
	s_nop 0
	v_mfma_f32_32x32x16_bf16 v[82:97], v[206:209], v[98:101], v[66:81]
	ds_read_b128 v[206:209], v172 offset:4672
	s_waitcnt lgkmcnt(4)
	v_mfma_f32_32x32x16_bf16 v[66:81], v[210:213], v[98:101], v[66:81]
	ds_read_b128 v[210:213], v172 offset:96
	s_waitcnt lgkmcnt(4)
	v_mfma_f32_32x32x16_bf16 v[82:97], v[222:225], v[102:105], v[82:97]
	ds_read_b128 v[222:225], v172 offset:4704
	s_waitcnt lgkmcnt(4)
	v_mfma_f32_32x32x16_bf16 v[66:81], v[238:241], v[102:105], v[66:81]
	s_waitcnt lgkmcnt(3)
	v_mfma_f32_32x32x16_bf16 v[82:97], v[242:245], v[106:109], v[82:97]
	s_waitcnt lgkmcnt(2)
	v_mfma_f32_32x32x16_bf16 v[66:81], v[206:209], v[106:109], v[66:81]
	s_waitcnt lgkmcnt(1)
	v_mfma_f32_32x32x16_bf16 v[82:97], v[210:213], v[110:113], v[82:97]
	s_waitcnt lgkmcnt(0)
	v_mfma_f32_32x32x16_bf16 v[66:81], v[222:225], v[110:113], v[66:81]
	s_nop 0
	v_add3_u32 v246, s5, v150, v186
	v_add_u32_e32 v246, 0x4800, v246
	v_add_u32_e32 v247, 0x1000, v246
	v_add_u32_e32 v248, 0x2000, v246
	v_add_u32_e32 v249, 0x3000, v246
	ds_read2_b64 v[192:195], v246 offset0:0 offset1:2
	ds_read2_b64 v[206:209], v247 offset0:32 offset1:34
	ds_read2_b64 v[210:213], v248 offset0:64 offset1:66
	ds_read2_b64 v[222:225], v249 offset0:96 offset1:98
	s_mov_b64 s[20:21], 0x2000
	v_lshl_add_u64 v[156:157], v[156:157], 0, s[20:21]
	v_lshl_add_u64 v[158:159], v[158:159], 0, s[20:21]
	s_mov_b64 s[20:21], 0x80
	v_lshl_add_u64 v[160:161], v[160:161], 0, s[20:21]
	v_lshl_add_u64 v[162:163], v[162:163], 0, s[20:21]
	v_lshl_add_u64 v[164:165], v[164:165], 0, s[20:21]
	v_lshl_add_u64 v[166:167], v[166:167], 0, s[20:21]
	s_nop 3
	v_max3_f32 v168, v66, v67, v68
	v_max3_f32 v169, v69, v70, v71
	v_max3_f32 v168, v168, v72, v73
	v_max3_f32 v169, v169, v74, v75
	v_max3_f32 v168, v168, v76, v77
	v_max3_f32 v169, v169, v78, v79
	v_max3_f32 v168, v168, v80, v81
	v_max3_f32 v169, v169, v82, v83
	v_max3_f32 v168, v168, v84, v85
	v_max3_f32 v169, v169, v86, v87
	v_max3_f32 v168, v168, v88, v89
	v_max3_f32 v169, v169, v90, v91
	v_max3_f32 v168, v168, v92, v93
	v_max3_f32 v169, v169, v94, v95
	v_max3_f32 v168, v168, v96, v97
	v_max_f32_e32 v168, v168, v169
	v_mov_b32_e32 v169, v168
	s_mov_b32 s20, 0x41000000
	s_nop 1
	v_permlane32_swap_b32_e32 v168, v169
	v_max_f32_e32 v168, v168, v169
	v_cmp_lt_f32_e32 vcc, s20, v168
	s_cbranch_vccz .LBB0_269
	v_max_f32_e32 v168, v168, v168
	v_max_f32_e32 v168, 0, v168
	v_add_f32_e32 v169, v154, v168
	v_sub_f32_e32 v154, v169, v154
	v_mov_b32_e32 v170, v82
	v_mov_b32_e32 v171, v66
	v_mov_b32_e32 v82, v83
	v_mov_b32_e32 v83, v84
	v_mov_b32_e32 v66, v67
	v_mov_b32_e32 v67, v68
	v_pk_add_f32 v[172:173], v[82:83], v[154:155] op_sel_hi:[1,0] neg_lo:[0,1] neg_hi:[0,1]
	v_pk_add_f32 v[82:83], v[66:67], v[154:155] op_sel_hi:[1,0] neg_lo:[0,1] neg_hi:[0,1]
	v_mov_b32_e32 v66, v85
	v_mov_b32_e32 v67, v86
	v_pk_add_f32 v[174:175], v[66:67], v[154:155] op_sel_hi:[1,0] neg_lo:[0,1] neg_hi:[0,1]
	v_mov_b32_e32 v66, v69
	v_mov_b32_e32 v67, v70
	v_pk_add_f32 v[84:85], v[66:67], v[154:155] op_sel_hi:[1,0] neg_lo:[0,1] neg_hi:[0,1]
	v_mov_b32_e32 v66, v87
	v_mov_b32_e32 v67, v88
	v_pk_add_f32 v[176:177], v[66:67], v[154:155] op_sel_hi:[1,0] neg_lo:[0,1] neg_hi:[0,1]
	v_mov_b32_e32 v66, v71
	v_mov_b32_e32 v67, v72
	v_pk_add_f32 v[86:87], v[66:67], v[154:155] op_sel_hi:[1,0] neg_lo:[0,1] neg_hi:[0,1]
	v_mov_b32_e32 v66, v89
	v_mov_b32_e32 v67, v90
	v_pk_add_f32 v[178:179], v[66:67], v[154:155] op_sel_hi:[1,0] neg_lo:[0,1] neg_hi:[0,1]
	v_mov_b32_e32 v66, v73
	v_mov_b32_e32 v67, v74
	v_pk_add_f32 v[88:89], v[66:67], v[154:155] op_sel_hi:[1,0] neg_lo:[0,1] neg_hi:[0,1]
	v_mov_b32_e32 v66, v91
	v_mov_b32_e32 v67, v92
	v_pk_add_f32 v[180:181], v[66:67], v[154:155] op_sel_hi:[1,0] neg_lo:[0,1] neg_hi:[0,1]
	v_mov_b32_e32 v66, v75
	v_mov_b32_e32 v67, v76
	v_pk_add_f32 v[90:91], v[66:67], v[154:155] op_sel_hi:[1,0] neg_lo:[0,1] neg_hi:[0,1]
	v_mov_b32_e32 v66, v93
	v_mov_b32_e32 v67, v94
	v_exp_f32_e64 v168, -v154
	v_pk_add_f32 v[188:189], v[66:67], v[154:155] op_sel_hi:[1,0] neg_lo:[0,1] neg_hi:[0,1]
	v_mov_b32_e32 v66, v77
	v_mov_b32_e32 v67, v78
	v_pk_add_f32 v[92:93], v[66:67], v[154:155] op_sel_hi:[1,0] neg_lo:[0,1] neg_hi:[0,1]
	v_mov_b32_e32 v66, v95
	v_mov_b32_e32 v67, v96
	v_pk_add_f32 v[190:191], v[66:67], v[154:155] op_sel_hi:[1,0] neg_lo:[0,1] neg_hi:[0,1]
	v_mov_b32_e32 v66, v79
	v_mov_b32_e32 v67, v80
	v_pk_add_f32 v[170:171], v[170:171], v[154:155] op_sel_hi:[1,0] neg_lo:[0,1] neg_hi:[0,1]
	v_pk_add_f32 v[94:95], v[66:67], v[154:155] op_sel_hi:[1,0] neg_lo:[0,1] neg_hi:[0,1]
	v_pk_mul_f32 v[64:65], v[64:65], v[168:169] op_sel_hi:[1,0]
	v_pk_mul_f32 v[62:63], v[62:63], v[168:169] op_sel_hi:[1,0]
	v_pk_mul_f32 v[60:61], v[60:61], v[168:169] op_sel_hi:[1,0]
	v_pk_mul_f32 v[58:59], v[58:59], v[168:169] op_sel_hi:[1,0]
	v_pk_mul_f32 v[56:57], v[56:57], v[168:169] op_sel_hi:[1,0]
	v_pk_mul_f32 v[54:55], v[54:55], v[168:169] op_sel_hi:[1,0]
	v_pk_mul_f32 v[52:53], v[52:53], v[168:169] op_sel_hi:[1,0]
	v_pk_mul_f32 v[50:51], v[50:51], v[168:169] op_sel_hi:[1,0]
	v_pk_mul_f32 v[48:49], v[48:49], v[168:169] op_sel_hi:[1,0]
	v_pk_mul_f32 v[46:47], v[46:47], v[168:169] op_sel_hi:[1,0]
	v_pk_mul_f32 v[44:45], v[44:45], v[168:169] op_sel_hi:[1,0]
	v_pk_mul_f32 v[42:43], v[42:43], v[168:169] op_sel_hi:[1,0]
	v_pk_mul_f32 v[40:41], v[40:41], v[168:169] op_sel_hi:[1,0]
	v_pk_mul_f32 v[38:39], v[38:39], v[168:169] op_sel_hi:[1,0]
	v_pk_mul_f32 v[36:37], v[36:37], v[168:169] op_sel_hi:[1,0]
	v_pk_mul_f32 v[34:35], v[34:35], v[168:169] op_sel_hi:[1,0]
	v_pk_mul_f32 v[32:33], v[32:33], v[168:169] op_sel_hi:[1,0]
	v_pk_mul_f32 v[30:31], v[30:31], v[168:169] op_sel_hi:[1,0]
	v_pk_mul_f32 v[28:29], v[28:29], v[168:169] op_sel_hi:[1,0]
	v_pk_mul_f32 v[26:27], v[26:27], v[168:169] op_sel_hi:[1,0]
	v_pk_mul_f32 v[24:25], v[24:25], v[168:169] op_sel_hi:[1,0]
	v_pk_mul_f32 v[22:23], v[22:23], v[168:169] op_sel_hi:[1,0]
	v_pk_mul_f32 v[20:21], v[20:21], v[168:169] op_sel_hi:[1,0]
	v_pk_mul_f32 v[18:19], v[18:19], v[168:169] op_sel_hi:[1,0]
	v_pk_mul_f32 v[16:17], v[16:17], v[168:169] op_sel_hi:[1,0]
	v_pk_mul_f32 v[14:15], v[14:15], v[168:169] op_sel_hi:[1,0]
	v_pk_mul_f32 v[12:13], v[12:13], v[168:169] op_sel_hi:[1,0]
	v_pk_mul_f32 v[10:11], v[10:11], v[168:169] op_sel_hi:[1,0]
	v_pk_mul_f32 v[8:9], v[8:9], v[168:169] op_sel_hi:[1,0]
	v_pk_mul_f32 v[6:7], v[6:7], v[168:169] op_sel_hi:[1,0]
	v_pk_mul_f32 v[4:5], v[4:5], v[168:169] op_sel_hi:[1,0]
	v_pk_mul_f32 v[2:3], v[2:3], v[168:169] op_sel_hi:[1,0]
	v_sub_f32_e32 v97, v97, v154
	v_sub_f32_e32 v81, v81, v154
	v_mul_f32_e32 v185, v185, v168
	v_mov_b32_e32 v154, v169
	v_mov_b32_e32 v67, v82
	v_mov_b32_e32 v68, v83
	v_mov_b32_e32 v69, v84
	v_mov_b32_e32 v70, v85
	v_mov_b32_e32 v71, v86
	v_mov_b32_e32 v72, v87
	v_mov_b32_e32 v73, v88
	v_mov_b32_e32 v74, v89
	v_mov_b32_e32 v75, v90
	v_mov_b32_e32 v76, v91
	v_mov_b32_e32 v77, v92
	v_mov_b32_e32 v78, v93
	v_mov_b32_e32 v79, v94
	v_mov_b32_e32 v80, v95
	v_mov_b32_e32 v83, v172
	v_mov_b32_e32 v84, v173
	v_mov_b32_e32 v85, v174
	v_mov_b32_e32 v86, v175
	v_mov_b32_e32 v87, v176
	v_mov_b32_e32 v88, v177
	v_mov_b32_e32 v89, v178
	v_mov_b32_e32 v90, v179
	v_mov_b32_e32 v91, v180
	v_mov_b32_e32 v92, v181
	v_mov_b32_e32 v93, v188
	v_mov_b32_e32 v94, v189
	v_mov_b32_e32 v95, v190
	v_mov_b32_e32 v96, v191
	v_mov_b32_e32 v82, v170
	v_mov_b32_e32 v66, v171
.LBB0_269:
	v_exp_f32_e32 v180, v82
	v_exp_f32_e32 v181, v66
	v_exp_f32_e32 v178, v83
	v_exp_f32_e32 v179, v67
	v_exp_f32_e32 v176, v84
	v_exp_f32_e32 v177, v68
	v_exp_f32_e32 v174, v85
	v_exp_f32_e32 v175, v69
	v_exp_f32_e32 v172, v86
	v_exp_f32_e32 v173, v70
	v_exp_f32_e32 v170, v87
	v_exp_f32_e32 v171, v71
	v_exp_f32_e32 v168, v88
	v_exp_f32_e32 v169, v72
	v_exp_f32_e32 v88, v89
	v_exp_f32_e32 v89, v73
	v_exp_f32_e32 v86, v90
	v_exp_f32_e32 v87, v74
	v_exp_f32_e32 v84, v91
	v_exp_f32_e32 v85, v75
	v_exp_f32_e32 v82, v92
	v_exp_f32_e32 v83, v76
	v_exp_f32_e32 v74, v93
	v_exp_f32_e32 v75, v77
	v_exp_f32_e32 v72, v94
	v_exp_f32_e32 v73, v78
	v_exp_f32_e32 v70, v95
	v_exp_f32_e32 v71, v79
	v_exp_f32_e32 v68, v96
	v_exp_f32_e32 v69, v80
	v_exp_f32_e32 v66, v97
	v_exp_f32_e32 v67, v81
	v_cvt_pk_bf16_f32 v76, v180, v178
	v_cvt_pk_bf16_f32 v77, v176, v174
	v_cvt_pk_bf16_f32 v78, v172, v170
	v_cvt_pk_bf16_f32 v79, v168, v88
	v_cvt_pk_bf16_f32 v90, v86, v84
	v_cvt_pk_bf16_f32 v91, v82, v74
	v_cvt_pk_bf16_f32 v92, v72, v70
	v_cvt_pk_bf16_f32 v93, v68, v66
	v_cvt_pk_bf16_f32 v94, v181, v179
	v_cvt_pk_bf16_f32 v95, v177, v175
	v_cvt_pk_bf16_f32 v96, v173, v171
	v_cvt_pk_bf16_f32 v97, v169, v89
	v_cvt_pk_bf16_f32 v188, v87, v85
	v_cvt_pk_bf16_f32 v189, v83, v75
	v_cvt_pk_bf16_f32 v190, v73, v71
	v_cvt_pk_bf16_f32 v191, v69, v67
	s_nop 0
	s_waitcnt lgkmcnt(3)
	v_mfma_f32_32x32x16_bf16 v[50:65], v[192:195], v[76:79], v[50:65]
	ds_read2_b64 v[192:195], v246 offset0:4 offset1:6
	s_add_i32 s5, s4, -1
	s_bitcmp1_b32 s5, 0
	s_cselect_b32 s5, 0x8c00, 0
	v_add_f32_e32 v238, v180, v181
	v_add_f32_e32 v239, v172, v173
	s_waitcnt lgkmcnt(3)
	v_mfma_f32_32x32x16_bf16 v[34:49], v[206:209], v[76:79], v[34:49]
	ds_read2_b64 v[206:209], v247 offset0:36 offset1:38
	v_lshlrev_b32_e32 v250, 1, v153
	v_add3_u32 v250, s5, v250, v152
	v_add_f32_e32 v240, v86, v87
	v_add_f32_e32 v241, v72, v73
	s_waitcnt lgkmcnt(3)
	v_mfma_f32_32x32x16_bf16 v[18:33], v[210:213], v[76:79], v[18:33]
	ds_read2_b64 v[210:213], v248 offset0:68 offset1:70
	s_waitcnt vmcnt(0)
	ds_write_b128 v250, v[114:117]
	v_add_f32_e32 v238, v238, v178
	v_add_f32_e32 v239, v239, v170
	s_waitcnt lgkmcnt(4)
	v_mfma_f32_32x32x16_bf16 v[2:17], v[222:225], v[76:79], v[2:17]
	ds_read2_b64 v[222:225], v249 offset0:100 offset1:102
	ds_write_b128 v250, v[118:121] offset:4608
	v_add_f32_e32 v240, v240, v84
	v_add_f32_e32 v241, v241, v70
	s_waitcnt lgkmcnt(5)
	v_mfma_f32_32x32x16_bf16 v[50:65], v[192:195], v[90:93], v[50:65]
	ds_read2_b64 v[192:195], v246 offset0:8 offset1:10
	ds_write_b128 v250, v[122:125] offset:9216
	v_add_f32_e32 v238, v238, v179
	v_add_f32_e32 v239, v239, v171
	s_waitcnt lgkmcnt(6)
	v_mfma_f32_32x32x16_bf16 v[34:49], v[206:209], v[90:93], v[34:49]
	ds_read2_b64 v[206:209], v247 offset0:40 offset1:42
	ds_write_b128 v250, v[126:129] offset:13824
	v_add_f32_e32 v240, v240, v85
	v_add_f32_e32 v241, v241, v71
	s_waitcnt lgkmcnt(7)
	v_mfma_f32_32x32x16_bf16 v[18:33], v[210:213], v[90:93], v[18:33]
	ds_read2_b64 v[210:213], v248 offset0:72 offset1:74
	v_lshlrev_b32_e32 v251, 1, v182
	v_add3_u32 v251, s5, v251, v152
	v_add_f32_e32 v238, v238, v176
	v_add_f32_e32 v239, v239, v168
	s_waitcnt lgkmcnt(6)
	v_mfma_f32_32x32x16_bf16 v[2:17], v[222:225], v[90:93], v[2:17]
	ds_read2_b64 v[222:225], v249 offset0:104 offset1:106
	v_add_u32_e32 v214, 0x4800, v251
	ds_write2_b64 v214, v[130:131], v[132:133] offset1:1
	v_add_f32_e32 v240, v240, v82
	v_add_f32_e32 v241, v241, v68
	s_waitcnt lgkmcnt(6)
	v_mfma_f32_32x32x16_bf16 v[50:65], v[192:195], v[94:97], v[50:65]
	ds_read2_b64 v[192:195], v246 offset0:12 offset1:14
	v_add_u32_e32 v214, 0x5900, v251
	ds_write2_b64 v214, v[134:135], v[136:137] offset1:1
	v_add_f32_e32 v238, v238, v177
	v_add_f32_e32 v239, v239, v169
	s_waitcnt lgkmcnt(6)
	v_mfma_f32_32x32x16_bf16 v[34:49], v[206:209], v[94:97], v[34:49]
	ds_read2_b64 v[206:209], v247 offset0:44 offset1:46
	v_add_u32_e32 v214, 0x6a00, v251
	ds_write2_b64 v214, v[138:139], v[140:141] offset1:1
	v_add_f32_e32 v240, v240, v83
	v_add_f32_e32 v241, v241, v69
	s_waitcnt lgkmcnt(6)
	v_mfma_f32_32x32x16_bf16 v[18:33], v[210:213], v[94:97], v[18:33]
	ds_read2_b64 v[210:213], v248 offset0:76 offset1:78
	v_add_u32_e32 v214, 0x7b00, v251
	ds_write2_b64 v214, v[142:143], v[144:145] offset1:1
	v_add_f32_e32 v238, v238, v174
	v_add_f32_e32 v239, v239, v88
	s_waitcnt lgkmcnt(7)
	v_mfma_f32_32x32x16_bf16 v[2:17], v[222:225], v[94:97], v[2:17]
	ds_read2_b64 v[222:225], v249 offset0:108 offset1:110
	global_load_dwordx4 v[114:117], v[156:157], off offset:-2048
	global_load_dwordx4 v[118:121], v[156:157], off offset:2048
	v_add_f32_e32 v240, v240, v74
	v_add_f32_e32 v241, v241, v66
	s_waitcnt lgkmcnt(6)
	v_mfma_f32_32x32x16_bf16 v[50:65], v[192:195], v[188:191], v[50:65]
	global_load_dwordx4 v[122:125], v[158:159], off offset:-2048
	global_load_dwordx4 v[126:129], v[158:159], off offset:2048
	v_add_f32_e32 v238, v238, v175
	v_add_f32_e32 v239, v239, v89
	s_waitcnt lgkmcnt(4)
	v_mfma_f32_32x32x16_bf16 v[34:49], v[206:209], v[188:191], v[34:49]
	global_load_dwordx4 v[130:133], v[160:161], off offset:384
	global_load_dwordx4 v[134:137], v[162:163], off offset:384
	v_add_f32_e32 v240, v240, v75
	v_add_f32_e32 v241, v241, v67
	s_waitcnt lgkmcnt(2)
	v_mfma_f32_32x32x16_bf16 v[18:33], v[210:213], v[188:191], v[18:33]
	global_load_dwordx4 v[138:141], v[164:165], off offset:384
	global_load_dwordx4 v[142:145], v[166:167], off offset:384
	v_add_f32_e32 v238, v238, v239
	v_add_f32_e32 v240, v240, v241
	s_waitcnt lgkmcnt(0)
	v_mfma_f32_32x32x16_bf16 v[2:17], v[222:225], v[188:191], v[2:17]
	v_add_f32_e32 v238, v238, v240
	s_nop 0
	s_branch .LBB0_266
